# A3 scan-carry chains: one unified loop, 32 chunks (dwordx2 of the needed component pair) per batch instead of 8-chunk batches with up to 3 exposed round trips; same fma order
# speedup vs baseline: 1.0584x; 1.0016x over previous
; __device__ __forceinline__ void seq_of(int s, int& start, int& len) { if (s < 4) { start = s * SP; len = SP; } else { start = MP + (s - 4) * SS; len = SS; } }
; __global__ void __launch_bounds__(512) mega_fwd(Params P) {
;     ...
;             if (wave < 2) for (int w = (G - 1 - bx) * 2 + wave; w < 128; w += 2 * G) {
;                 const int dir = w & 1, cid = (w >> 1) * 64 + lane, s = cid >> 9, ch = cid & 511; int st, len; seq_of(s, st, len); const int c0 = st / 32, nc = len / 32; float carry = 0.f;
;                 if (dir == 0) { for (int cb = c0; cb < c0 + nc; cb += 8) { f32x4 sm[8];
.LBB0_1037:
	s_bfe_u32 s38, s57, 0x30006
	v_lshl_or_b32 v194, s38, 9, v16
	v_lshl_or_b32 v18, s38, 10, v17
	s_ashr_i32 s38, s56, 4
	s_lshl_b32 s39, s38, 11
	s_addk_i32 s39, 0x6000
	s_lshl_b32 s40, s38, 13
	s_cmp_lt_i32 s38, 4
	s_cselect_b32 s38, s40, s39
	s_cselect_b32 s39, 0x100, 64
	s_ashr_i32 s48, s38, 5
	s_add_i32 s52, s48, s39
	s_sub_i32 s53, s52, s48
	s_add_i32 s49, s52, -1
	s_cmp_lg_u32 s46, 0
	s_cselect_b32 s49, s49, s48
	s_movk_i32 s38, 0x2000
	s_cselect_b32 s38, 0xffffe000, s38
	s_cselect_b32 s39, -1, 0
	s_movk_i32 s40, 0x1000
	s_cselect_b32 s40, 0xfffff000, s40
	s_cselect_b32 s41, -1, 0
	s_mov_b32 s54, 0xf00000
	s_cselect_b32 s54, 0xf00008, s54
	s_mov_b32 s55, 0x1900000
	s_cselect_b32 s55, 0x1900004, s55
	v_mov_b32_e32 v0, v18
	v_mov_b32_e32 v1, v195
	v_mov_b32_e32 v2, v194
	v_mov_b32_e32 v3, v195
	v_lshl_add_u64 v[0:1], s[44:45], 0, v[0:1]
	v_lshl_add_u64 v[2:3], s[44:45], 0, v[2:3]
	s_lshl_b32 s49, s49, 12
	s_add_u32 s55, s55, s49
	s_lshl_b32 s49, s49, 1
	s_add_u32 s54, s54, s49
	s_mov_b32 s49, 0
	v_mov_b32_e32 v6, s54
	v_mov_b32_e32 v7, s49
	v_mov_b32_e32 v8, s55
	v_mov_b32_e32 v9, s49
	v_lshl_add_u64 v[0:1], v[0:1], 0, v[6:7]
	v_lshl_add_u64 v[2:3], v[2:3], 0, v[8:9]
	v_mov_b32_e32 v4, 0
; __global__ void __launch_bounds__(512) mega_fwd(Params P) {
;     ...
;                 if (dir == 0) { for (int cb = c0; cb < c0 + nc; cb += 8) { f32x4 sm[8];
; #pragma unroll
;                         for (int k = 0; k < 8; ++k) sm[k] = *(const f32x4*)(SSUM + ((size_t)(cb + k) * 512 + ch) * 4);
; #pragma unroll
;                         for (int k = 0; k < 8; ++k) { SCAR[((size_t)(cb + k) * 512 + ch) * 2] = carry; carry = sm[k].x * carry + sm[k].y; } } }
;                 else { for (int cb = c0 + nc - 8; cb >= c0; cb -= 8) { f32x4 sm[8];
; #pragma unroll
;                         for (int k = 0; k < 8; ++k) sm[k] = *(const f32x4*)(SSUM + ((size_t)(cb + k) * 512 + ch) * 4);
; #pragma unroll
;                         for (int k = 7; k >= 0; --k) { SCAR[((size_t)(cb + k) * 512 + ch) * 2 + 1] = carry; carry = sm[k].z * carry + sm[k].w; } } }
.Lmy_carry_batch:
	global_load_dwordx2 v[20:21], v[0:1], off
	v_lshl_add_u64 v[0:1], v[0:1], 0, s[38:39]
	global_load_dwordx2 v[22:23], v[0:1], off
	v_lshl_add_u64 v[0:1], v[0:1], 0, s[38:39]
	global_load_dwordx2 v[24:25], v[0:1], off
	v_lshl_add_u64 v[0:1], v[0:1], 0, s[38:39]
	global_load_dwordx2 v[26:27], v[0:1], off
	v_lshl_add_u64 v[0:1], v[0:1], 0, s[38:39]
	global_load_dwordx2 v[28:29], v[0:1], off
	v_lshl_add_u64 v[0:1], v[0:1], 0, s[38:39]
	global_load_dwordx2 v[30:31], v[0:1], off
	v_lshl_add_u64 v[0:1], v[0:1], 0, s[38:39]
	global_load_dwordx2 v[32:33], v[0:1], off
	v_lshl_add_u64 v[0:1], v[0:1], 0, s[38:39]
	global_load_dwordx2 v[34:35], v[0:1], off
	v_lshl_add_u64 v[0:1], v[0:1], 0, s[38:39]
	global_load_dwordx2 v[36:37], v[0:1], off
	v_lshl_add_u64 v[0:1], v[0:1], 0, s[38:39]
	global_load_dwordx2 v[38:39], v[0:1], off
	v_lshl_add_u64 v[0:1], v[0:1], 0, s[38:39]
	global_load_dwordx2 v[40:41], v[0:1], off
	v_lshl_add_u64 v[0:1], v[0:1], 0, s[38:39]
	global_load_dwordx2 v[42:43], v[0:1], off
	v_lshl_add_u64 v[0:1], v[0:1], 0, s[38:39]
	global_load_dwordx2 v[44:45], v[0:1], off
	v_lshl_add_u64 v[0:1], v[0:1], 0, s[38:39]
	global_load_dwordx2 v[46:47], v[0:1], off
	v_lshl_add_u64 v[0:1], v[0:1], 0, s[38:39]
	global_load_dwordx2 v[48:49], v[0:1], off
	v_lshl_add_u64 v[0:1], v[0:1], 0, s[38:39]
	global_load_dwordx2 v[50:51], v[0:1], off
	v_lshl_add_u64 v[0:1], v[0:1], 0, s[38:39]
	global_load_dwordx2 v[52:53], v[0:1], off
	v_lshl_add_u64 v[0:1], v[0:1], 0, s[38:39]
	global_load_dwordx2 v[54:55], v[0:1], off
	v_lshl_add_u64 v[0:1], v[0:1], 0, s[38:39]
	global_load_dwordx2 v[56:57], v[0:1], off
	v_lshl_add_u64 v[0:1], v[0:1], 0, s[38:39]
	global_load_dwordx2 v[58:59], v[0:1], off
	v_lshl_add_u64 v[0:1], v[0:1], 0, s[38:39]
	global_load_dwordx2 v[60:61], v[0:1], off
	v_lshl_add_u64 v[0:1], v[0:1], 0, s[38:39]
	global_load_dwordx2 v[62:63], v[0:1], off
	v_lshl_add_u64 v[0:1], v[0:1], 0, s[38:39]
	global_load_dwordx2 v[64:65], v[0:1], off
	v_lshl_add_u64 v[0:1], v[0:1], 0, s[38:39]
	global_load_dwordx2 v[66:67], v[0:1], off
	v_lshl_add_u64 v[0:1], v[0:1], 0, s[38:39]
	global_load_dwordx2 v[68:69], v[0:1], off
	v_lshl_add_u64 v[0:1], v[0:1], 0, s[38:39]
	global_load_dwordx2 v[70:71], v[0:1], off
	v_lshl_add_u64 v[0:1], v[0:1], 0, s[38:39]
	global_load_dwordx2 v[72:73], v[0:1], off
	v_lshl_add_u64 v[0:1], v[0:1], 0, s[38:39]
	global_load_dwordx2 v[74:75], v[0:1], off
	v_lshl_add_u64 v[0:1], v[0:1], 0, s[38:39]
	global_load_dwordx2 v[76:77], v[0:1], off
	v_lshl_add_u64 v[0:1], v[0:1], 0, s[38:39]
	global_load_dwordx2 v[78:79], v[0:1], off
	v_lshl_add_u64 v[0:1], v[0:1], 0, s[38:39]
	global_load_dwordx2 v[80:81], v[0:1], off
	v_lshl_add_u64 v[0:1], v[0:1], 0, s[38:39]
	global_load_dwordx2 v[82:83], v[0:1], off
	v_lshl_add_u64 v[0:1], v[0:1], 0, s[38:39]
	s_waitcnt vmcnt(0)
	global_store_dword v[2:3], v4, off
	v_fmac_f32_e32 v21, v4, v20
	v_lshl_add_u64 v[2:3], v[2:3], 0, s[40:41]
	global_store_dword v[2:3], v21, off
	v_fmac_f32_e32 v23, v21, v22
	v_lshl_add_u64 v[2:3], v[2:3], 0, s[40:41]
	global_store_dword v[2:3], v23, off
	v_fmac_f32_e32 v25, v23, v24
	v_lshl_add_u64 v[2:3], v[2:3], 0, s[40:41]
	global_store_dword v[2:3], v25, off
	v_fmac_f32_e32 v27, v25, v26
	v_lshl_add_u64 v[2:3], v[2:3], 0, s[40:41]
	global_store_dword v[2:3], v27, off
	v_fmac_f32_e32 v29, v27, v28
	v_lshl_add_u64 v[2:3], v[2:3], 0, s[40:41]
	global_store_dword v[2:3], v29, off
	v_fmac_f32_e32 v31, v29, v30
	v_lshl_add_u64 v[2:3], v[2:3], 0, s[40:41]
	global_store_dword v[2:3], v31, off
	v_fmac_f32_e32 v33, v31, v32
	v_lshl_add_u64 v[2:3], v[2:3], 0, s[40:41]
	global_store_dword v[2:3], v33, off
	v_fmac_f32_e32 v35, v33, v34
	v_lshl_add_u64 v[2:3], v[2:3], 0, s[40:41]
	global_store_dword v[2:3], v35, off
	v_fmac_f32_e32 v37, v35, v36
	v_lshl_add_u64 v[2:3], v[2:3], 0, s[40:41]
	global_store_dword v[2:3], v37, off
	v_fmac_f32_e32 v39, v37, v38
	v_lshl_add_u64 v[2:3], v[2:3], 0, s[40:41]
	global_store_dword v[2:3], v39, off
	v_fmac_f32_e32 v41, v39, v40
	v_lshl_add_u64 v[2:3], v[2:3], 0, s[40:41]
	global_store_dword v[2:3], v41, off
	v_fmac_f32_e32 v43, v41, v42
	v_lshl_add_u64 v[2:3], v[2:3], 0, s[40:41]
	global_store_dword v[2:3], v43, off
	v_fmac_f32_e32 v45, v43, v44
	v_lshl_add_u64 v[2:3], v[2:3], 0, s[40:41]
	global_store_dword v[2:3], v45, off
	v_fmac_f32_e32 v47, v45, v46
	v_lshl_add_u64 v[2:3], v[2:3], 0, s[40:41]
	global_store_dword v[2:3], v47, off
	v_fmac_f32_e32 v49, v47, v48
	v_lshl_add_u64 v[2:3], v[2:3], 0, s[40:41]
	global_store_dword v[2:3], v49, off
	v_fmac_f32_e32 v51, v49, v50
	v_lshl_add_u64 v[2:3], v[2:3], 0, s[40:41]
	global_store_dword v[2:3], v51, off
	v_fmac_f32_e32 v53, v51, v52
	v_lshl_add_u64 v[2:3], v[2:3], 0, s[40:41]
	global_store_dword v[2:3], v53, off
	v_fmac_f32_e32 v55, v53, v54
	v_lshl_add_u64 v[2:3], v[2:3], 0, s[40:41]
	global_store_dword v[2:3], v55, off
	v_fmac_f32_e32 v57, v55, v56
	v_lshl_add_u64 v[2:3], v[2:3], 0, s[40:41]
	global_store_dword v[2:3], v57, off
	v_fmac_f32_e32 v59, v57, v58
	v_lshl_add_u64 v[2:3], v[2:3], 0, s[40:41]
	global_store_dword v[2:3], v59, off
	v_fmac_f32_e32 v61, v59, v60
	v_lshl_add_u64 v[2:3], v[2:3], 0, s[40:41]
	global_store_dword v[2:3], v61, off
	v_fmac_f32_e32 v63, v61, v62
	v_lshl_add_u64 v[2:3], v[2:3], 0, s[40:41]
	global_store_dword v[2:3], v63, off
	v_fmac_f32_e32 v65, v63, v64
	v_lshl_add_u64 v[2:3], v[2:3], 0, s[40:41]
	global_store_dword v[2:3], v65, off
	v_fmac_f32_e32 v67, v65, v66
	v_lshl_add_u64 v[2:3], v[2:3], 0, s[40:41]
	global_store_dword v[2:3], v67, off
	v_fmac_f32_e32 v69, v67, v68
	v_lshl_add_u64 v[2:3], v[2:3], 0, s[40:41]
	global_store_dword v[2:3], v69, off
	v_fmac_f32_e32 v71, v69, v70
	v_lshl_add_u64 v[2:3], v[2:3], 0, s[40:41]
	global_store_dword v[2:3], v71, off
	v_fmac_f32_e32 v73, v71, v72
	v_lshl_add_u64 v[2:3], v[2:3], 0, s[40:41]
	global_store_dword v[2:3], v73, off
	v_fmac_f32_e32 v75, v73, v74
	v_lshl_add_u64 v[2:3], v[2:3], 0, s[40:41]
	global_store_dword v[2:3], v75, off
	v_fmac_f32_e32 v77, v75, v76
	v_lshl_add_u64 v[2:3], v[2:3], 0, s[40:41]
	global_store_dword v[2:3], v77, off
	v_fmac_f32_e32 v79, v77, v78
	v_lshl_add_u64 v[2:3], v[2:3], 0, s[40:41]
	global_store_dword v[2:3], v79, off
	v_fmac_f32_e32 v81, v79, v80
	v_lshl_add_u64 v[2:3], v[2:3], 0, s[40:41]
	global_store_dword v[2:3], v81, off
	v_fmac_f32_e32 v83, v81, v82
	v_lshl_add_u64 v[2:3], v[2:3], 0, s[40:41]
	v_mov_b32_e32 v4, v83
	s_sub_i32 s53, s53, 32
	s_cmp_gt_i32 s53, 0
	s_cbranch_scc1 .Lmy_carry_batch
	s_branch .LBB0_1036
